# fused GEMM epilogue: part-1 and part-2 vector/residual loads issued before the row-exchange's final barrier (overlap load latency with the barrier)
# speedup vs baseline: 1.0039x; 1.0039x over previous
; #define LAS __attribute__((address_space(3)))
; __device__ __forceinline__ void row_exchange(const f32x4 (&v)[2][2][4][2], const Unit& u, int wr, int wc, int fr, int fq, LAS unsigned char* lds, int wid, int lane, float* slots, unsigned* cnt) {
;     ...
;     asm volatile("s_waitcnt vmcnt(0) lgkmcnt(0)" ::: "memory"); __builtin_amdgcn_s_barrier(); asm volatile("" ::: "memory");
; }
;     __device__ __forceinline__ void fused(f32x4 (&acc)[2][2][4][2], const Unit& u, int wr, int wc, int fr, int fq, LAS unsigned char* lds, int wid, int lane) const {
;         const LAS float* S = (const LAS float*)(lds + 4096);
;         const int col0 = u.pn * BM + wc * 32 + 4 * fq; const size_t mb = (size_t)(u.pm >> 4) * (NMOD * D);
;         row_exchange(acc, u, wr, wc, fr, fq, lds, wid, lane, slots, cnt);
;         {
;             f32x4 cw[2][2];
; #pragma unroll
;             for (int bj = 0; bj < 2; ++bj)
; #pragma unroll
;                 for (int n = 0; n < 2; ++n) cw[bj][n] = *(const f32x4*)(gate + mb + col0 + bj * HALF + n * 16) * *(const f32x4*)(gpost + col0 + bj * HALF + n * 16);
; #pragma unroll
;             for (int ai = 0; ai < 2; ++ai)
; #pragma unroll
;                 for (int m = 0; m < 4; ++m) { const int r = ai * HALF + wr * 64 + m * 16 + fr; const float r1 = rsqrtf(S[r] * (1.0f / D) + EPS) * wgt; const size_t off = (size_t)(u.pm * BM + r) * D + col0;
; #pragma unroll
;                     for (int bj = 0; bj < 2; ++bj)
; #pragma unroll
;                         for (int n = 0; n < 2; ++n) { const f32x4 xv = *(const f32x4*)(xin + off + bj * HALF + n * 16); const f32x4 xn = xv + (cw[bj][n] * r1) * acc[ai][bj][m][n];
;                             acc[ai][bj][m][n] = xn; *(f32x4*)(xout + off + bj * HALF + n * 16) = xn; }
;                     asm volatile("" : "+v"(acc[ai][0][m][0]), "+v"(acc[ai][0][m][1]), "+v"(acc[ai][1][m][0]), "+v"(acc[ai][1][m][1]));
;                     asm volatile("" ::: "memory"); }
.LBB0_1116:
	s_or_b64 exec, exec, s[48:49]
	v_readlane_b32 s18, v253, 36
	s_lshl_b32 s0, s15, 5
	s_lshl_b32 s1, s86, 8
	s_mul_i32 s15, s18, 45
	s_or_b32 s0, s1, s0
	v_lshrrev_b32_e32 v128, 2, v138
	s_add_i32 s15, s12, s15
	v_and_or_b32 v154, v128, 12, s0
	s_ashr_i32 s0, s33, 4
	s_lshl_b32 s15, s15, 12
	s_mul_hi_i32 s1, s0, 0x2400
	s_mulk_i32 s0, 0x2400
	s_add_u32 s15, s94, s15
	s_addc_u32 s18, s95, 0
	s_lshl_b64 s[94:95], s[0:1], 2
	s_add_u32 s0, s15, s94
	v_ashrrev_i32_e32 v155, 31, v154
	s_addc_u32 s1, s18, s95
	v_lshlrev_b64 v[128:129], 2, v[154:155]
	v_lshl_add_u64 v[132:133], s[0:1], 0, v[128:129]
	s_mov_b64 s[0:1], 0xa300000
	v_lshl_add_u64 v[162:163], v[132:133], 0, s[0:1]
	v_readlane_b32 s0, v253, 43
	v_readlane_b32 s1, v253, 44
	v_lshl_add_u32 v208, v156, 2, 0
	v_lshl_add_u64 v[164:165], s[0:1], 0, v[128:129]
	s_mov_b32 s0, 0xa300000
	s_cmp_eq_u64 s[30:31], 0
	v_readlane_b32 s19, v253, 37
	v_add_u32_e32 v158, s50, v156
	v_ashrrev_i32_e32 v159, 31, v158
	v_lshlrev_b64 v[246:247], 10, v[158:159]
	v_lshl_add_u64 v[246:247], v[246:247], 0, v[154:155]
	v_lshlrev_b64 v[246:247], 2, v[246:247]
	v_lshl_add_u64 v[246:247], s[90:91], 0, v[246:247]
	global_load_dwordx4 v[212:215], v[246:247], off
	global_load_dwordx4 v[216:219], v[246:247], off offset:64
	global_load_dwordx4 v[220:223], v[246:247], off offset:512
	global_load_dwordx4 v[224:227], v[246:247], off offset:576
	v_add_u32_e32 v156, 16, v158
	v_ashrrev_i32_e32 v157, 31, v156
	v_lshlrev_b64 v[246:247], 10, v[156:157]
	v_lshl_add_u64 v[246:247], v[246:247], 0, v[154:155]
	v_lshlrev_b64 v[246:247], 2, v[246:247]
	v_lshl_add_u64 v[246:247], s[90:91], 0, v[246:247]
	global_load_dwordx4 v[228:231], v[246:247], off
	global_load_dwordx4 v[232:235], v[246:247], off offset:64
	global_load_dwordx4 v[236:239], v[246:247], off offset:512
	global_load_dwordx4 v[240:243], v[246:247], off offset:576
	global_load_dwordx4 v[172:175], v[162:163], off
	global_load_dwordx4 v[180:183], v[164:165], off
	global_load_dwordx4 v[140:143], v[162:163], off offset:64
	global_load_dwordx4 v[184:187], v[164:165], off offset:64
	global_load_dwordx4 v[136:139], v[162:163], off offset:512
	global_load_dwordx4 v[244:247], v[164:165], off offset:512
	global_load_dwordx4 v[132:135], v[162:163], off offset:576
	global_load_dwordx4 v[166:169], v[164:165], off offset:576
	s_waitcnt lgkmcnt(0)
	s_barrier
	s_waitcnt vmcnt(0)
	v_pk_mul_f32 v[172:173], v[172:173], v[180:181]
	v_pk_mul_f32 v[174:175], v[174:175], v[182:183]
	v_pk_mul_f32 v[140:141], v[140:141], v[184:185]
	v_pk_mul_f32 v[142:143], v[142:143], v[186:187]
	v_pk_mul_f32 v[136:137], v[136:137], v[244:245]
	v_pk_mul_f32 v[138:139], v[138:139], v[246:247]
	v_pk_mul_f32 v[132:133], v[132:133], v[166:167]
	v_pk_mul_f32 v[134:135], v[134:135], v[168:169]
	ds_read_b32 v144, v208 offset:4096
	v_lshlrev_b64 v[180:181], 10, v[158:159]
	v_lshl_add_u64 v[180:181], v[180:181], 0, v[154:155]
	v_lshlrev_b64 v[180:181], 2, v[180:181]
	v_lshl_add_u64 v[182:183], s[88:89], 0, v[180:181]
	s_waitcnt lgkmcnt(0)
	v_fmamk_f32 v144, v144, 0x3a800000, v146
	v_cmp_gt_f32_e32 vcc, s67, v144
	v_mul_f32_e32 v244, 0x4b800000, v144
	s_nop 0
	v_cndmask_b32_e32 v144, v144, v244, vcc
	v_rsq_f32_e32 v144, v144
	s_nop 0
	v_mul_f32_e32 v244, 0x45800000, v144
	v_cndmask_b32_e32 v144, v144, v244, vcc
	v_mul_f32_e32 v144, v149, v144
	v_pk_mul_f32 v[184:185], v[172:173], v[144:145] op_sel_hi:[1,0]
	v_pk_mul_f32 v[186:187], v[174:175], v[144:145] op_sel_hi:[1,0]
	v_pk_fma_f32 v[88:89], v[88:89], v[184:185], v[212:213]
	v_pk_fma_f32 v[90:91], v[90:91], v[186:187], v[214:215]
	global_store_dwordx4 v[182:183], v[88:91], off
	v_pk_mul_f32 v[184:185], v[140:141], v[144:145] op_sel_hi:[1,0]
	v_pk_mul_f32 v[186:187], v[142:143], v[144:145] op_sel_hi:[1,0]
	v_pk_fma_f32 v[104:105], v[104:105], v[184:185], v[216:217]
	v_pk_fma_f32 v[106:107], v[106:107], v[186:187], v[218:219]
	global_store_dwordx4 v[182:183], v[104:107], off offset:64
	v_pk_mul_f32 v[184:185], v[136:137], v[144:145] op_sel_hi:[1,0]
	v_pk_mul_f32 v[186:187], v[138:139], v[144:145] op_sel_hi:[1,0]
	v_pk_fma_f32 v[100:101], v[100:101], v[184:185], v[220:221]
	v_pk_fma_f32 v[102:103], v[102:103], v[186:187], v[222:223]
	global_store_dwordx4 v[182:183], v[100:103], off offset:512
	v_pk_mul_f32 v[184:185], v[132:133], v[144:145] op_sel_hi:[1,0]
	v_pk_mul_f32 v[186:187], v[134:135], v[144:145] op_sel_hi:[1,0]
	v_pk_fma_f32 v[84:85], v[84:85], v[184:185], v[224:225]
	v_pk_fma_f32 v[86:87], v[86:87], v[186:187], v[226:227]
	global_store_dwordx4 v[182:183], v[84:87], off offset:576
	v_add_u32_e32 v160, 32, v158
	v_ashrrev_i32_e32 v161, 31, v160
	v_lshlrev_b64 v[246:247], 10, v[160:161]
	v_lshl_add_u64 v[246:247], v[246:247], 0, v[154:155]
	v_lshlrev_b64 v[246:247], 2, v[246:247]
	v_lshl_add_u64 v[246:247], s[90:91], 0, v[246:247]
	global_load_dwordx4 v[212:215], v[246:247], off
	global_load_dwordx4 v[216:219], v[246:247], off offset:64
	global_load_dwordx4 v[220:223], v[246:247], off offset:512
	global_load_dwordx4 v[224:227], v[246:247], off offset:576
	ds_read_b32 v144, v208 offset:4160
	v_lshlrev_b64 v[180:181], 10, v[156:157]
	v_lshl_add_u64 v[180:181], v[180:181], 0, v[154:155]
	v_lshlrev_b64 v[180:181], 2, v[180:181]
	v_lshl_add_u64 v[182:183], s[88:89], 0, v[180:181]
	s_waitcnt lgkmcnt(0)
;     __device__ __forceinline__ void fused(f32x4 (&acc)[2][2][4][2], const Unit& u, int wr, int wc, int fr, int fq, LAS unsigned char* lds, int wid, int lane) const {
;     ...
; #pragma unroll
;                 for (int m = 0; m < 4; ++m) { const int r = ai * HALF + wr * 64 + m * 16 + fr; const float r1 = rsqrtf(S[r] * (1.0f / D) + EPS) * wgt; const size_t off = (size_t)(u.pm * BM + r) * D + col0;
; #pragma unroll
;                     for (int bj = 0; bj < 2; ++bj)
; #pragma unroll
;                         for (int n = 0; n < 2; ++n) { const f32x4 xv = *(const f32x4*)(xin + off + bj * HALF + n * 16); const f32x4 xn = xv + (cw[bj][n] * r1) * acc[ai][bj][m][n];
;                             acc[ai][bj][m][n] = xn; *(f32x4*)(xout + off + bj * HALF + n * 16) = xn; }
;                     asm volatile("" : "+v"(acc[ai][0][m][0]), "+v"(acc[ai][0][m][1]), "+v"(acc[ai][1][m][0]), "+v"(acc[ai][1][m][1]));
;                     asm volatile("" ::: "memory"); }
	v_fmamk_f32 v144, v144, 0x3a800000, v146
	v_cmp_gt_f32_e32 vcc, s67, v144
	v_mul_f32_e32 v244, 0x4b800000, v144
	s_nop 0
	v_cndmask_b32_e32 v144, v144, v244, vcc
	v_rsq_f32_e32 v144, v144
	s_nop 0
	v_mul_f32_e32 v244, 0x45800000, v144
	v_cndmask_b32_e32 v144, v144, v244, vcc
	v_mul_f32_e32 v144, v149, v144
	v_pk_mul_f32 v[184:185], v[172:173], v[144:145] op_sel_hi:[1,0]
	v_pk_mul_f32 v[186:187], v[174:175], v[144:145] op_sel_hi:[1,0]
	v_pk_fma_f32 v[76:77], v[76:77], v[184:185], v[228:229]
	v_pk_fma_f32 v[78:79], v[78:79], v[186:187], v[230:231]
	global_store_dwordx4 v[182:183], v[76:79], off
	v_pk_mul_f32 v[184:185], v[140:141], v[144:145] op_sel_hi:[1,0]
	v_pk_mul_f32 v[186:187], v[142:143], v[144:145] op_sel_hi:[1,0]
	v_pk_fma_f32 v[92:93], v[92:93], v[184:185], v[232:233]
	v_pk_fma_f32 v[94:95], v[94:95], v[186:187], v[234:235]
	global_store_dwordx4 v[182:183], v[92:95], off offset:64
	v_pk_mul_f32 v[184:185], v[136:137], v[144:145] op_sel_hi:[1,0]
	v_pk_mul_f32 v[186:187], v[138:139], v[144:145] op_sel_hi:[1,0]
	v_pk_fma_f32 v[80:81], v[80:81], v[184:185], v[236:237]
	v_pk_fma_f32 v[82:83], v[82:83], v[186:187], v[238:239]
	global_store_dwordx4 v[182:183], v[80:83], off offset:512
	v_pk_mul_f32 v[184:185], v[132:133], v[144:145] op_sel_hi:[1,0]
	v_pk_mul_f32 v[186:187], v[134:135], v[144:145] op_sel_hi:[1,0]
	v_pk_fma_f32 v[72:73], v[72:73], v[184:185], v[240:241]
	v_pk_fma_f32 v[74:75], v[74:75], v[186:187], v[242:243]
	global_store_dwordx4 v[182:183], v[72:75], off offset:576
	v_add_u32_e32 v162, 48, v158
	v_ashrrev_i32_e32 v163, 31, v162
	v_lshlrev_b64 v[246:247], 10, v[162:163]
	v_lshl_add_u64 v[246:247], v[246:247], 0, v[154:155]
	v_lshlrev_b64 v[246:247], 2, v[246:247]
	v_lshl_add_u64 v[246:247], s[90:91], 0, v[246:247]
	global_load_dwordx4 v[228:231], v[246:247], off
	global_load_dwordx4 v[232:235], v[246:247], off offset:64
	global_load_dwordx4 v[236:239], v[246:247], off offset:512
	global_load_dwordx4 v[240:243], v[246:247], off offset:576
	ds_read_b32 v144, v208 offset:4224
	v_lshlrev_b64 v[180:181], 10, v[160:161]
	v_lshl_add_u64 v[180:181], v[180:181], 0, v[154:155]
	v_lshlrev_b64 v[180:181], 2, v[180:181]
	v_lshl_add_u64 v[182:183], s[88:89], 0, v[180:181]
	s_waitcnt lgkmcnt(0)
	v_fmamk_f32 v144, v144, 0x3a800000, v146
	v_cmp_gt_f32_e32 vcc, s67, v144
	v_mul_f32_e32 v244, 0x4b800000, v144
	s_nop 0
	v_cndmask_b32_e32 v144, v144, v244, vcc
	v_rsq_f32_e32 v144, v144
	s_nop 0
	v_mul_f32_e32 v244, 0x45800000, v144
	v_cndmask_b32_e32 v144, v144, v244, vcc
	v_mul_f32_e32 v144, v149, v144
	s_waitcnt vmcnt(8)
	v_pk_mul_f32 v[184:185], v[172:173], v[144:145] op_sel_hi:[1,0]
	v_pk_mul_f32 v[186:187], v[174:175], v[144:145] op_sel_hi:[1,0]
	v_pk_fma_f32 v[108:109], v[108:109], v[184:185], v[212:213]
	v_pk_fma_f32 v[110:111], v[110:111], v[186:187], v[214:215]
	global_store_dwordx4 v[182:183], v[108:111], off
	v_pk_mul_f32 v[184:185], v[140:141], v[144:145] op_sel_hi:[1,0]
	v_pk_mul_f32 v[186:187], v[142:143], v[144:145] op_sel_hi:[1,0]
	v_pk_fma_f32 v[124:125], v[124:125], v[184:185], v[216:217]
	v_pk_fma_f32 v[126:127], v[126:127], v[186:187], v[218:219]
	global_store_dwordx4 v[182:183], v[124:127], off offset:64
	v_pk_mul_f32 v[184:185], v[136:137], v[144:145] op_sel_hi:[1,0]
	v_pk_mul_f32 v[186:187], v[138:139], v[144:145] op_sel_hi:[1,0]
	v_pk_fma_f32 v[120:121], v[120:121], v[184:185], v[220:221]
	v_pk_fma_f32 v[122:123], v[122:123], v[186:187], v[222:223]
	global_store_dwordx4 v[182:183], v[120:123], off offset:512
	v_pk_mul_f32 v[184:185], v[132:133], v[144:145] op_sel_hi:[1,0]
	v_pk_mul_f32 v[186:187], v[134:135], v[144:145] op_sel_hi:[1,0]
	v_pk_fma_f32 v[116:117], v[116:117], v[184:185], v[224:225]
	v_pk_fma_f32 v[118:119], v[118:119], v[186:187], v[226:227]
	global_store_dwordx4 v[182:183], v[116:119], off offset:576
	v_add_u32_e32 v164, 0x80, v158
	v_ashrrev_i32_e32 v165, 31, v164
	v_lshlrev_b64 v[246:247], 10, v[164:165]
	v_lshl_add_u64 v[246:247], v[246:247], 0, v[154:155]
	v_lshlrev_b64 v[246:247], 2, v[246:247]
	v_lshl_add_u64 v[246:247], s[90:91], 0, v[246:247]
	global_load_dwordx4 v[212:215], v[246:247], off
	global_load_dwordx4 v[216:219], v[246:247], off offset:64
	global_load_dwordx4 v[220:223], v[246:247], off offset:512
	global_load_dwordx4 v[224:227], v[246:247], off offset:576
	ds_read_b32 v144, v208 offset:4288
	v_lshlrev_b64 v[180:181], 10, v[162:163]
	v_lshl_add_u64 v[180:181], v[180:181], 0, v[154:155]
	v_lshlrev_b64 v[180:181], 2, v[180:181]
	v_lshl_add_u64 v[182:183], s[88:89], 0, v[180:181]
	s_waitcnt lgkmcnt(0)
	v_fmamk_f32 v144, v144, 0x3a800000, v146
	v_cmp_gt_f32_e32 vcc, s67, v144
	v_mul_f32_e32 v244, 0x4b800000, v144
	s_nop 0
	v_cndmask_b32_e32 v144, v144, v244, vcc
	v_rsq_f32_e32 v144, v144
	s_nop 0
	v_mul_f32_e32 v244, 0x45800000, v144
	v_cndmask_b32_e32 v144, v144, v244, vcc
	v_mul_f32_e32 v144, v149, v144
	s_waitcnt vmcnt(8)
;     __device__ __forceinline__ void fused(f32x4 (&acc)[2][2][4][2], const Unit& u, int wr, int wc, int fr, int fq, LAS unsigned char* lds, int wid, int lane) const {
;     ...
; #pragma unroll
;                 for (int m = 0; m < 4; ++m) { const int r = ai * HALF + wr * 64 + m * 16 + fr; const float r1 = rsqrtf(S[r] * (1.0f / D) + EPS) * wgt; const size_t off = (size_t)(u.pm * BM + r) * D + col0;
; #pragma unroll
;                     for (int bj = 0; bj < 2; ++bj)
; #pragma unroll
;                         for (int n = 0; n < 2; ++n) { const f32x4 xv = *(const f32x4*)(xin + off + bj * HALF + n * 16); const f32x4 xn = xv + (cw[bj][n] * r1) * acc[ai][bj][m][n];
;                             acc[ai][bj][m][n] = xn; *(f32x4*)(xout + off + bj * HALF + n * 16) = xn; }
;                     asm volatile("" : "+v"(acc[ai][0][m][0]), "+v"(acc[ai][0][m][1]), "+v"(acc[ai][1][m][0]), "+v"(acc[ai][1][m][1]));
;                     asm volatile("" ::: "memory"); }
	v_pk_mul_f32 v[184:185], v[172:173], v[144:145] op_sel_hi:[1,0]
	v_pk_mul_f32 v[186:187], v[174:175], v[144:145] op_sel_hi:[1,0]
	v_pk_fma_f32 v[112:113], v[112:113], v[184:185], v[228:229]
	v_pk_fma_f32 v[114:115], v[114:115], v[186:187], v[230:231]
	global_store_dwordx4 v[182:183], v[112:115], off
	v_pk_mul_f32 v[184:185], v[140:141], v[144:145] op_sel_hi:[1,0]
	v_pk_mul_f32 v[186:187], v[142:143], v[144:145] op_sel_hi:[1,0]
	v_pk_fma_f32 v[96:97], v[96:97], v[184:185], v[232:233]
	v_pk_fma_f32 v[98:99], v[98:99], v[186:187], v[234:235]
	global_store_dwordx4 v[182:183], v[96:99], off offset:64
	v_pk_mul_f32 v[184:185], v[136:137], v[144:145] op_sel_hi:[1,0]
	v_pk_mul_f32 v[186:187], v[138:139], v[144:145] op_sel_hi:[1,0]
	v_pk_fma_f32 v[68:69], v[68:69], v[184:185], v[236:237]
	v_pk_fma_f32 v[70:71], v[70:71], v[186:187], v[238:239]
	global_store_dwordx4 v[182:183], v[68:71], off offset:512
	v_pk_mul_f32 v[184:185], v[132:133], v[144:145] op_sel_hi:[1,0]
	v_pk_mul_f32 v[186:187], v[134:135], v[144:145] op_sel_hi:[1,0]
	v_pk_fma_f32 v[64:65], v[64:65], v[184:185], v[240:241]
	v_pk_fma_f32 v[66:67], v[66:67], v[186:187], v[242:243]
	global_store_dwordx4 v[182:183], v[64:67], off offset:576
	v_add_u32_e32 v166, 0x90, v158
	v_ashrrev_i32_e32 v167, 31, v166
	v_lshlrev_b64 v[246:247], 10, v[166:167]
	v_lshl_add_u64 v[246:247], v[246:247], 0, v[154:155]
	v_lshlrev_b64 v[246:247], 2, v[246:247]
	v_lshl_add_u64 v[246:247], s[90:91], 0, v[246:247]
	global_load_dwordx4 v[228:231], v[246:247], off
	global_load_dwordx4 v[232:235], v[246:247], off offset:64
	global_load_dwordx4 v[236:239], v[246:247], off offset:512
	global_load_dwordx4 v[240:243], v[246:247], off offset:576
	ds_read_b32 v144, v208 offset:4608
	v_lshlrev_b64 v[180:181], 10, v[164:165]
	v_lshl_add_u64 v[180:181], v[180:181], 0, v[154:155]
	v_lshlrev_b64 v[180:181], 2, v[180:181]
	v_lshl_add_u64 v[182:183], s[88:89], 0, v[180:181]
	s_waitcnt lgkmcnt(0)
	v_fmamk_f32 v144, v144, 0x3a800000, v146
	v_cmp_gt_f32_e32 vcc, s67, v144
	v_mul_f32_e32 v244, 0x4b800000, v144
	s_nop 0
	v_cndmask_b32_e32 v144, v144, v244, vcc
	v_rsq_f32_e32 v144, v144
	s_nop 0
	v_mul_f32_e32 v244, 0x45800000, v144
	v_cndmask_b32_e32 v144, v144, v244, vcc
	v_mul_f32_e32 v144, v149, v144
	s_waitcnt vmcnt(8)
	v_pk_mul_f32 v[184:185], v[172:173], v[144:145] op_sel_hi:[1,0]
	v_pk_mul_f32 v[186:187], v[174:175], v[144:145] op_sel_hi:[1,0]
	v_pk_fma_f32 v[60:61], v[60:61], v[184:185], v[212:213]
	v_pk_fma_f32 v[62:63], v[62:63], v[186:187], v[214:215]
	global_store_dwordx4 v[182:183], v[60:63], off
	v_pk_mul_f32 v[184:185], v[140:141], v[144:145] op_sel_hi:[1,0]
	v_pk_mul_f32 v[186:187], v[142:143], v[144:145] op_sel_hi:[1,0]
	v_pk_fma_f32 v[56:57], v[56:57], v[184:185], v[216:217]
	v_pk_fma_f32 v[58:59], v[58:59], v[186:187], v[218:219]
	global_store_dwordx4 v[182:183], v[56:59], off offset:64
	v_pk_mul_f32 v[184:185], v[136:137], v[144:145] op_sel_hi:[1,0]
	v_pk_mul_f32 v[186:187], v[138:139], v[144:145] op_sel_hi:[1,0]
	v_pk_fma_f32 v[52:53], v[52:53], v[184:185], v[220:221]
	v_pk_fma_f32 v[54:55], v[54:55], v[186:187], v[222:223]
	global_store_dwordx4 v[182:183], v[52:55], off offset:512
	v_pk_mul_f32 v[184:185], v[132:133], v[144:145] op_sel_hi:[1,0]
	v_pk_mul_f32 v[186:187], v[134:135], v[144:145] op_sel_hi:[1,0]
	v_pk_fma_f32 v[48:49], v[48:49], v[184:185], v[224:225]
	v_pk_fma_f32 v[50:51], v[50:51], v[186:187], v[226:227]
	global_store_dwordx4 v[182:183], v[48:51], off offset:576
	v_add_u32_e32 v168, 0xa0, v158
	v_ashrrev_i32_e32 v169, 31, v168
	v_lshlrev_b64 v[246:247], 10, v[168:169]
	v_lshl_add_u64 v[246:247], v[246:247], 0, v[154:155]
	v_lshlrev_b64 v[246:247], 2, v[246:247]
	v_lshl_add_u64 v[246:247], s[90:91], 0, v[246:247]
	global_load_dwordx4 v[212:215], v[246:247], off
	global_load_dwordx4 v[216:219], v[246:247], off offset:64
	global_load_dwordx4 v[220:223], v[246:247], off offset:512
	global_load_dwordx4 v[224:227], v[246:247], off offset:576
	ds_read_b32 v144, v208 offset:4672
	v_lshlrev_b64 v[180:181], 10, v[166:167]
	v_lshl_add_u64 v[180:181], v[180:181], 0, v[154:155]
	v_lshlrev_b64 v[180:181], 2, v[180:181]
	v_lshl_add_u64 v[182:183], s[88:89], 0, v[180:181]
	s_waitcnt lgkmcnt(0)
	v_fmamk_f32 v144, v144, 0x3a800000, v146
	v_cmp_gt_f32_e32 vcc, s67, v144
	v_mul_f32_e32 v244, 0x4b800000, v144
	s_nop 0
	v_cndmask_b32_e32 v144, v144, v244, vcc
	v_rsq_f32_e32 v144, v144
	s_nop 0
	v_mul_f32_e32 v244, 0x45800000, v144
	v_cndmask_b32_e32 v144, v144, v244, vcc
	v_mul_f32_e32 v144, v149, v144
	s_waitcnt vmcnt(8)
; __device__ __forceinline__ void row_exchange(const f32x4 (&v)[2][2][4][2], const Unit& u, int wr, int wc, int fr, int fq, LAS unsigned char* lds, int wid, int lane, float* slots, unsigned* cnt) {
;     ...
;             float sq = 0.f;
; #pragma unroll
;             for (int bj = 0; bj < 2; ++bj)
; #pragma unroll
;                 for (int n = 0; n < 2; ++n) { const f32x4 x = v[ai][bj][m][n]; sq += (x[0] * x[0] + x[1] * x[1]) + (x[2] * x[2] + x[3] * x[3]); }
;             sq += __shfl_xor(sq, 16); sq += __shfl_xor(sq, 32);
;             if (fq == 0) P[(ai * HALF + wr * 64 + m * 16 + fr) * 4 + wc] = sq;
;     __device__ __forceinline__ void fused(f32x4 (&acc)[2][2][4][2], const Unit& u, int wr, int wc, int fr, int fq, LAS unsigned char* lds, int wid, int lane) const {
;     ...
; #pragma unroll
;                 for (int m = 0; m < 4; ++m) { const int r = ai * HALF + wr * 64 + m * 16 + fr; const float r1 = rsqrtf(S[r] * (1.0f / D) + EPS) * wgt; const size_t off = (size_t)(u.pm * BM + r) * D + col0;
; #pragma unroll
;                     for (int bj = 0; bj < 2; ++bj)
; #pragma unroll
;                         for (int n = 0; n < 2; ++n) { const f32x4 xv = *(const f32x4*)(xin + off + bj * HALF + n * 16); const f32x4 xn = xv + (cw[bj][n] * r1) * acc[ai][bj][m][n];
;                             acc[ai][bj][m][n] = xn; *(f32x4*)(xout + off + bj * HALF + n * 16) = xn; }
;                     asm volatile("" : "+v"(acc[ai][0][m][0]), "+v"(acc[ai][0][m][1]), "+v"(acc[ai][1][m][0]), "+v"(acc[ai][1][m][1]));
;                     asm volatile("" ::: "memory"); }
;         }
;         if (H == nullptr) return;
;         row_exchange(acc, u, wr, wc, fr, fq, lds, wid, lane, slots + (size_t)TL * 4, cnt + 64 * 64);
	v_pk_mul_f32 v[184:185], v[172:173], v[144:145] op_sel_hi:[1,0]
	v_pk_mul_f32 v[186:187], v[174:175], v[144:145] op_sel_hi:[1,0]
	v_pk_fma_f32 v[44:45], v[44:45], v[184:185], v[228:229]
	v_pk_fma_f32 v[46:47], v[46:47], v[186:187], v[230:231]
	global_store_dwordx4 v[182:183], v[44:47], off
	v_pk_mul_f32 v[184:185], v[140:141], v[144:145] op_sel_hi:[1,0]
	v_pk_mul_f32 v[186:187], v[142:143], v[144:145] op_sel_hi:[1,0]
	v_pk_fma_f32 v[40:41], v[40:41], v[184:185], v[232:233]
	v_pk_fma_f32 v[42:43], v[42:43], v[186:187], v[234:235]
	global_store_dwordx4 v[182:183], v[40:43], off offset:64
	v_pk_mul_f32 v[184:185], v[136:137], v[144:145] op_sel_hi:[1,0]
	v_pk_mul_f32 v[186:187], v[138:139], v[144:145] op_sel_hi:[1,0]
	v_pk_fma_f32 v[36:37], v[36:37], v[184:185], v[236:237]
	v_pk_fma_f32 v[38:39], v[38:39], v[186:187], v[238:239]
	global_store_dwordx4 v[182:183], v[36:39], off offset:512
	v_pk_mul_f32 v[184:185], v[132:133], v[144:145] op_sel_hi:[1,0]
	v_pk_mul_f32 v[186:187], v[134:135], v[144:145] op_sel_hi:[1,0]
	v_pk_fma_f32 v[32:33], v[32:33], v[184:185], v[240:241]
	v_pk_fma_f32 v[34:35], v[34:35], v[186:187], v[242:243]
	global_store_dwordx4 v[182:183], v[32:35], off offset:576
	v_add_u32_e32 v170, 0xb0, v158
	v_ashrrev_i32_e32 v171, 31, v170
	v_lshlrev_b64 v[246:247], 10, v[170:171]
	v_lshl_add_u64 v[246:247], v[246:247], 0, v[154:155]
	v_lshlrev_b64 v[246:247], 2, v[246:247]
	v_lshl_add_u64 v[246:247], s[90:91], 0, v[246:247]
	global_load_dwordx4 v[228:231], v[246:247], off
	global_load_dwordx4 v[232:235], v[246:247], off offset:64
	global_load_dwordx4 v[236:239], v[246:247], off offset:512
	global_load_dwordx4 v[240:243], v[246:247], off offset:576
	ds_read_b32 v144, v208 offset:4736
	v_lshlrev_b64 v[180:181], 10, v[168:169]
	v_lshl_add_u64 v[180:181], v[180:181], 0, v[154:155]
	v_lshlrev_b64 v[180:181], 2, v[180:181]
	v_lshl_add_u64 v[182:183], s[88:89], 0, v[180:181]
	s_waitcnt lgkmcnt(0)
	v_fmamk_f32 v144, v144, 0x3a800000, v146
	v_cmp_gt_f32_e32 vcc, s67, v144
	v_mul_f32_e32 v244, 0x4b800000, v144
	s_nop 0
	v_cndmask_b32_e32 v144, v144, v244, vcc
	v_rsq_f32_e32 v144, v144
	s_nop 0
	v_mul_f32_e32 v244, 0x45800000, v144
	v_cndmask_b32_e32 v144, v144, v244, vcc
	v_mul_f32_e32 v144, v149, v144
	s_waitcnt vmcnt(8)
	v_pk_mul_f32 v[184:185], v[172:173], v[144:145] op_sel_hi:[1,0]
	v_pk_mul_f32 v[186:187], v[174:175], v[144:145] op_sel_hi:[1,0]
	v_pk_fma_f32 v[28:29], v[28:29], v[184:185], v[212:213]
	v_pk_fma_f32 v[30:31], v[30:31], v[186:187], v[214:215]
	global_store_dwordx4 v[182:183], v[28:31], off
	v_pk_mul_f32 v[184:185], v[140:141], v[144:145] op_sel_hi:[1,0]
	v_pk_mul_f32 v[186:187], v[142:143], v[144:145] op_sel_hi:[1,0]
	v_pk_fma_f32 v[24:25], v[24:25], v[184:185], v[216:217]
	v_pk_fma_f32 v[26:27], v[26:27], v[186:187], v[218:219]
	global_store_dwordx4 v[182:183], v[24:27], off offset:64
	v_pk_mul_f32 v[184:185], v[136:137], v[144:145] op_sel_hi:[1,0]
	v_pk_mul_f32 v[186:187], v[138:139], v[144:145] op_sel_hi:[1,0]
	v_pk_fma_f32 v[20:21], v[20:21], v[184:185], v[220:221]
	v_pk_fma_f32 v[22:23], v[22:23], v[186:187], v[222:223]
	global_store_dwordx4 v[182:183], v[20:23], off offset:512
	v_pk_mul_f32 v[184:185], v[132:133], v[144:145] op_sel_hi:[1,0]
	v_pk_mul_f32 v[186:187], v[134:135], v[144:145] op_sel_hi:[1,0]
	v_pk_fma_f32 v[16:17], v[16:17], v[184:185], v[224:225]
	v_pk_fma_f32 v[18:19], v[18:19], v[186:187], v[226:227]
	global_store_dwordx4 v[182:183], v[16:19], off offset:576
	ds_read_b32 v144, v208 offset:4800
	v_lshlrev_b64 v[180:181], 10, v[170:171]
	v_lshl_add_u64 v[180:181], v[180:181], 0, v[154:155]
	v_lshlrev_b64 v[180:181], 2, v[180:181]
	v_lshl_add_u64 v[182:183], s[88:89], 0, v[180:181]
	s_waitcnt lgkmcnt(0)
	v_fmamk_f32 v144, v144, 0x3a800000, v146
	v_cmp_gt_f32_e32 vcc, s67, v144
	v_mul_f32_e32 v244, 0x4b800000, v144
	s_nop 0
	v_cndmask_b32_e32 v144, v144, v244, vcc
	v_rsq_f32_e32 v144, v144
	s_nop 0
	v_mul_f32_e32 v244, 0x45800000, v144
	v_cndmask_b32_e32 v144, v144, v244, vcc
	v_mul_f32_e32 v144, v149, v144
	s_waitcnt vmcnt(4)
	v_pk_mul_f32 v[184:185], v[172:173], v[144:145] op_sel_hi:[1,0]
	v_pk_mul_f32 v[186:187], v[174:175], v[144:145] op_sel_hi:[1,0]
	v_pk_fma_f32 v[12:13], v[12:13], v[184:185], v[228:229]
	v_pk_fma_f32 v[14:15], v[14:15], v[186:187], v[230:231]
	global_store_dwordx4 v[182:183], v[12:15], off
	v_pk_mul_f32 v[184:185], v[140:141], v[144:145] op_sel_hi:[1,0]
	v_pk_mul_f32 v[186:187], v[142:143], v[144:145] op_sel_hi:[1,0]
	v_pk_fma_f32 v[8:9], v[8:9], v[184:185], v[232:233]
	v_pk_fma_f32 v[10:11], v[10:11], v[186:187], v[234:235]
	global_store_dwordx4 v[182:183], v[8:11], off offset:64
	v_pk_mul_f32 v[184:185], v[136:137], v[144:145] op_sel_hi:[1,0]
	v_pk_mul_f32 v[186:187], v[138:139], v[144:145] op_sel_hi:[1,0]
	v_pk_fma_f32 v[4:5], v[4:5], v[184:185], v[236:237]
	v_pk_fma_f32 v[6:7], v[6:7], v[186:187], v[238:239]
	global_store_dwordx4 v[182:183], v[4:7], off offset:512
	v_pk_mul_f32 v[184:185], v[132:133], v[144:145] op_sel_hi:[1,0]
	v_pk_mul_f32 v[186:187], v[134:135], v[144:145] op_sel_hi:[1,0]
	v_pk_fma_f32 v[0:1], v[0:1], v[184:185], v[240:241]
	v_pk_fma_f32 v[2:3], v[2:3], v[186:187], v[242:243]
	global_store_dwordx4 v[182:183], v[0:3], off offset:576
	s_nop 1
	s_cbranch_scc1 .LBB0_1153
	v_mul_f32_e32 v132, v89, v89
	v_mul_f32_e32 v133, v91, v91
	v_fmac_f32_e32 v132, v88, v88
	v_fmac_f32_e32 v133, v90, v90
	v_add_f32_e32 v132, v132, v133
	v_mul_f32_e32 v133, v105, v105
	v_mul_f32_e32 v134, v107, v107
	v_fmac_f32_e32 v133, v104, v104
	v_fmac_f32_e32 v134, v106, v106
	v_add_f32_e32 v133, v133, v134
	v_add_f32_e32 v132, v132, v133
	v_mul_f32_e32 v133, v101, v101
	v_mul_f32_e32 v134, v103, v103
	v_fmac_f32_e32 v133, v100, v100
	v_fmac_f32_e32 v134, v102, v102
	v_add_f32_e32 v133, v133, v134
	v_add_f32_e32 v132, v133, v132
	v_mul_f32_e32 v133, v85, v85
	v_mul_f32_e32 v134, v87, v87
	v_fmac_f32_e32 v133, v84, v84
	v_fmac_f32_e32 v134, v86, v86
	v_add_f32_e32 v133, v133, v134
	v_add_f32_e32 v132, v133, v132
	ds_bpermute_b32 v133, v177, v132
	s_waitcnt lgkmcnt(0)
	v_add_f32_e32 v132, v132, v133
	ds_bpermute_b32 v133, v178, v132
	s_and_saveexec_b64 s[0:1], s[8:9]
	s_cbranch_execz .LBB0_1119
	s_lshl_b32 s15, s80, 10
	s_add_i32 s15, s52, s15
	s_waitcnt lgkmcnt(0)
	v_add_f32_e32 v132, v132, v133
	v_lshl_add_u32 v133, v176, 4, s15
	ds_write_b32 v133, v132

; __device__ __forceinline__ unsigned cvt_pk_bf16(float lo, float hi) { unsigned r; asm volatile("v_cvt_pk_bf16_f32 %0, %1, %2" : "=v"(r) : "v"(lo), "v"(hi)); return r; }
; __device__ __forceinline__ void row_exchange(const f32x4 (&v)[2][2][4][2], const Unit& u, int wr, int wc, int fr, int fq, LAS unsigned char* lds, int wid, int lane, float* slots, unsigned* cnt) {
;     ...
;     asm volatile("s_waitcnt vmcnt(0) lgkmcnt(0)" ::: "memory"); __builtin_amdgcn_s_barrier(); asm volatile("" ::: "memory");
;     __device__ __forceinline__ void fused(f32x4 (&acc)[2][2][4][2], const Unit& u, int wr, int wc, int fr, int fq, LAS unsigned char* lds, int wid, int lane) const {
;     ...
;         {
;             f32x4 gm[2][2], sh[2][2];
; #pragma unroll
;             for (int bj = 0; bj < 2; ++bj)
; #pragma unroll
;                 for (int n = 0; n < 2; ++n) { const int c = col0 + bj * HALF + n * 16; gm[bj][n] = *(const f32x4*)(gpre + c) * (*(const f32x4*)(scale + mb + c) + 1.0f); sh[bj][n] = *(const f32x4*)(shift + mb + c); }
; #pragma unroll
;             for (int ai = 0; ai < 2; ++ai)
; #pragma unroll
;                 for (int m = 0; m < 4; ++m) { const int r = ai * HALF + wr * 64 + m * 16 + fr; const float r2 = rsqrtf(S[r] * (1.0f / D) + EPS); const size_t off = (size_t)(u.pm * BM + r) * D + col0;
; #pragma unroll
;                     for (int bj = 0; bj < 2; ++bj)
; #pragma unroll
;                         for (int n = 0; n < 2; ++n) { const f32x4 hv = (acc[ai][bj][m][n] * r2) * gm[bj][n] + sh[bj][n];
;                             uint2 w2; w2.x = cvt_pk_bf16(hv[0], hv[1]); w2.y = cvt_pk_bf16(hv[2], hv[3]); *(uint2*)(H + off + bj * HALF + n * 16) = w2; }
.LBB0_1152:
	s_or_b64 exec, exec, s[6:7]
	v_readlane_b32 s6, v253, 51
	s_add_i32 s80, s6, s14
	s_lshl_b64 s[0:1], s[80:81], 12
	s_add_u32 s4, s36, s0
	s_addc_u32 s5, s37, s1
	s_add_i32 s80, s6, s16
	s_lshl_b64 s[0:1], s[80:81], 12
	s_add_u32 s0, s34, s0
	s_addc_u32 s1, s35, s1
	s_add_u32 s0, s0, s94
	v_readlane_b32 s6, v253, 45
	s_addc_u32 s1, s1, s95
	v_readlane_b32 s7, v253, 46
	v_lshl_add_u64 v[134:135], s[0:1], 0, v[128:129]
	s_mov_b32 s0, 0xa300000
	v_lshl_add_u64 v[184:185], s[6:7], 0, v[128:129]
	s_mov_b64 s[6:7], 0xa300000
	v_lshl_add_u64 v[186:187], v[134:135], 0, s[6:7]
	v_add_co_u32_e32 v134, vcc, s0, v134
	s_nop 1
	v_addc_co_u32_e32 v135, vcc, 0, v135, vcc
	s_add_u32 s4, s4, s94
	s_addc_u32 s5, s5, s95
	v_lshl_add_u64 v[128:129], s[4:5], 0, v[128:129]
	v_lshl_add_u64 v[192:193], v[128:129], 0, s[6:7]
	v_add_co_u32_e32 v128, vcc, s0, v128
	v_lshlrev_b64 v[158:159], 11, v[158:159]
	s_nop 0
	v_addc_co_u32_e32 v129, vcc, 0, v129, vcc
	global_load_dwordx4 v[212:215], v[134:135], off
	global_load_dwordx4 v[228:231], v[184:185], off
	global_load_dwordx4 v[216:219], v[186:187], off offset:64
	global_load_dwordx4 v[232:235], v[184:185], off offset:64
	global_load_dwordx4 v[220:223], v[186:187], off offset:512
	global_load_dwordx4 v[236:239], v[184:185], off offset:512
	global_load_dwordx4 v[224:227], v[186:187], off offset:576
	global_load_dwordx4 v[240:243], v[184:185], off offset:576
	global_load_dwordx4 v[128:131], v[128:129], off
	global_load_dwordx4 v[132:135], v[192:193], off offset:64
	global_load_dwordx4 v[136:139], v[192:193], off offset:512
	global_load_dwordx4 v[140:143], v[192:193], off offset:576
	s_waitcnt lgkmcnt(0)
	s_barrier
	s_nop 0
	ds_read_b32 v144, v208 offset:4096
	s_waitcnt vmcnt(4)
	v_pk_add_f32 v[214:215], v[214:215], 1.0 op_sel_hi:[1,0]
	v_pk_add_f32 v[212:213], v[212:213], 1.0 op_sel_hi:[1,0]
	v_pk_mul_f32 v[172:173], v[230:231], v[214:215]
	v_pk_mul_f32 v[174:175], v[228:229], v[212:213]
	v_pk_add_f32 v[218:219], v[218:219], 1.0 op_sel_hi:[1,0]
	v_pk_add_f32 v[216:217], v[216:217], 1.0 op_sel_hi:[1,0]
	v_pk_mul_f32 v[176:177], v[234:235], v[218:219]
	v_pk_mul_f32 v[178:179], v[232:233], v[216:217]
	v_pk_add_f32 v[222:223], v[222:223], 1.0 op_sel_hi:[1,0]
	v_pk_add_f32 v[220:221], v[220:221], 1.0 op_sel_hi:[1,0]
	v_pk_mul_f32 v[180:181], v[238:239], v[222:223]
	v_pk_mul_f32 v[182:183], v[236:237], v[220:221]
	v_pk_add_f32 v[226:227], v[226:227], 1.0 op_sel_hi:[1,0]
	v_pk_add_f32 v[224:225], v[224:225], 1.0 op_sel_hi:[1,0]
	v_pk_mul_f32 v[184:185], v[242:243], v[226:227]
	v_pk_mul_f32 v[186:187], v[240:241], v[224:225]
	s_waitcnt lgkmcnt(0)
	v_fmamk_f32 v144, v144, 0x3a800000, v146
	v_cmp_gt_f32_e32 vcc, s67, v144
	s_nop 0
	s_waitcnt vmcnt(0)
	v_mul_f32_e32 v192, 0x4b800000, v144
	v_cndmask_b32_e32 v144, v144, v192, vcc
	v_rsq_f32_e32 v144, v144
	s_nop 0
	v_mul_f32_e32 v192, 0x45800000, v144
	v_cndmask_b32_e32 v144, v144, v192, vcc
	v_pk_mul_f32 v[88:89], v[88:89], v[144:145] op_sel_hi:[1,0]
	v_pk_mul_f32 v[90:91], v[90:91], v[144:145] op_sel_hi:[1,0]
	v_pk_fma_f32 v[88:89], v[174:175], v[88:89], v[128:129]
	v_pk_fma_f32 v[90:91], v[172:173], v[90:91], v[130:131]
	v_cvt_pk_bf16_f32 v192, v88, v89
	v_lshlrev_b64 v[88:89], 1, v[154:155]
	v_cvt_pk_bf16_f32 v193, v90, v91
	v_lshl_add_u64 v[90:91], s[30:31], 0, v[158:159]
	v_pk_mul_f32 v[104:105], v[104:105], v[144:145] op_sel_hi:[1,0]
	v_pk_mul_f32 v[100:101], v[100:101], v[144:145] op_sel_hi:[1,0]
	v_pk_mul_f32 v[84:85], v[84:85], v[144:145] op_sel_hi:[1,0]
	v_lshl_add_u64 v[90:91], v[90:91], 0, v[88:89]
	v_pk_mul_f32 v[106:107], v[106:107], v[144:145] op_sel_hi:[1,0]
	v_pk_fma_f32 v[104:105], v[178:179], v[104:105], v[132:133]
	v_pk_mul_f32 v[102:103], v[102:103], v[144:145] op_sel_hi:[1,0]
	v_pk_fma_f32 v[100:101], v[182:183], v[100:101], v[136:137]
	v_pk_mul_f32 v[86:87], v[86:87], v[144:145] op_sel_hi:[1,0]
	global_store_dwordx2 v[90:91], v[192:193], off
	v_pk_fma_f32 v[106:107], v[176:177], v[106:107], v[134:135]
	v_cvt_pk_bf16_f32 v104, v104, v105
	v_pk_fma_f32 v[102:103], v[180:181], v[102:103], v[138:139]
	v_cvt_pk_bf16_f32 v105, v106, v107
	global_store_dwordx2 v[90:91], v[104:105], off offset:32
	v_cvt_pk_bf16_f32 v100, v100, v101
	v_cvt_pk_bf16_f32 v101, v102, v103
	global_store_dwordx2 v[90:91], v[100:101], off offset:256
	s_waitcnt lgkmcnt(0)
	s_waitcnt vmcnt(3)
	v_pk_fma_f32 v[84:85], v[186:187], v[84:85], v[140:141]
	v_pk_fma_f32 v[86:87], v[184:185], v[86:87], v[142:143]
	v_cvt_pk_bf16_f32 v84, v84, v85
	s_nop 0
	v_cvt_pk_bf16_f32 v85, v86, v87
	global_store_dwordx2 v[90:91], v[84:85], off offset:288
	ds_read_b32 v84, v208 offset:4160
	v_lshlrev_b64 v[86:87], 11, v[156:157]
	s_waitcnt lgkmcnt(0)
; __device__ __forceinline__ unsigned cvt_pk_bf16(float lo, float hi) { unsigned r; asm volatile("v_cvt_pk_bf16_f32 %0, %1, %2" : "=v"(r) : "v"(lo), "v"(hi)); return r; }
;     __device__ __forceinline__ void fused(f32x4 (&acc)[2][2][4][2], const Unit& u, int wr, int wc, int fr, int fq, LAS unsigned char* lds, int wid, int lane) const {
;     ...
;             for (int ai = 0; ai < 2; ++ai)
; #pragma unroll
;                 for (int m = 0; m < 4; ++m) { const int r = ai * HALF + wr * 64 + m * 16 + fr; const float r2 = rsqrtf(S[r] * (1.0f / D) + EPS); const size_t off = (size_t)(u.pm * BM + r) * D + col0;
; #pragma unroll
;                     for (int bj = 0; bj < 2; ++bj)
; #pragma unroll
;                         for (int n = 0; n < 2; ++n) { const f32x4 hv = (acc[ai][bj][m][n] * r2) * gm[bj][n] + sh[bj][n];
;                             uint2 w2; w2.x = cvt_pk_bf16(hv[0], hv[1]); w2.y = cvt_pk_bf16(hv[2], hv[3]); *(uint2*)(H + off + bj * HALF + n * 16) = w2; }
;                     asm volatile("" ::: "memory"); }
	v_fmamk_f32 v84, v84, 0x3a800000, v146
	v_cmp_gt_f32_e32 vcc, s67, v84
	v_mul_f32_e32 v85, 0x4b800000, v84
	s_nop 0
	v_cndmask_b32_e32 v84, v84, v85, vcc
	v_rsq_f32_e32 v84, v84
	s_nop 0
	v_mul_f32_e32 v85, 0x45800000, v84
	v_cndmask_b32_e32 v84, v84, v85, vcc
	v_pk_mul_f32 v[76:77], v[76:77], v[84:85] op_sel_hi:[1,0]
	v_pk_mul_f32 v[78:79], v[78:79], v[84:85] op_sel_hi:[1,0]
	v_pk_fma_f32 v[76:77], v[174:175], v[76:77], v[128:129]
	v_pk_fma_f32 v[78:79], v[172:173], v[78:79], v[130:131]
	v_cvt_pk_bf16_f32 v76, v76, v77
	v_pk_mul_f32 v[72:73], v[72:73], v[84:85] op_sel_hi:[1,0]
	v_cvt_pk_bf16_f32 v77, v78, v79
	v_lshl_add_u64 v[78:79], s[30:31], 0, v[86:87]
	v_lshl_add_u64 v[78:79], v[78:79], 0, v[88:89]
	global_store_dwordx2 v[78:79], v[76:77], off
	v_pk_mul_f32 v[76:77], v[92:93], v[84:85] op_sel_hi:[1,0]
	v_pk_mul_f32 v[86:87], v[94:95], v[84:85] op_sel_hi:[1,0]
	v_pk_fma_f32 v[76:77], v[178:179], v[76:77], v[132:133]
	v_pk_fma_f32 v[86:87], v[176:177], v[86:87], v[134:135]
	v_cvt_pk_bf16_f32 v76, v76, v77
	v_pk_mul_f32 v[74:75], v[74:75], v[84:85] op_sel_hi:[1,0]
	v_cvt_pk_bf16_f32 v77, v86, v87
	global_store_dwordx2 v[78:79], v[76:77], off offset:32
	v_pk_mul_f32 v[76:77], v[80:81], v[84:85] op_sel_hi:[1,0]
	v_pk_mul_f32 v[80:81], v[82:83], v[84:85] op_sel_hi:[1,0]
	v_pk_fma_f32 v[76:77], v[182:183], v[76:77], v[136:137]
	v_pk_fma_f32 v[72:73], v[186:187], v[72:73], v[140:141]
	v_pk_fma_f32 v[80:81], v[180:181], v[80:81], v[138:139]
	v_cvt_pk_bf16_f32 v76, v76, v77
	v_pk_fma_f32 v[74:75], v[184:185], v[74:75], v[142:143]
	v_cvt_pk_bf16_f32 v77, v80, v81
	global_store_dwordx2 v[78:79], v[76:77], off offset:256
	v_cvt_pk_bf16_f32 v72, v72, v73
	v_cvt_pk_bf16_f32 v73, v74, v75
	global_store_dwordx2 v[78:79], v[72:73], off offset:288
	ds_read_b32 v72, v208 offset:4224
	v_lshlrev_b64 v[74:75], 11, v[160:161]
	v_lshl_add_u64 v[74:75], s[30:31], 0, v[74:75]
	v_lshl_add_u64 v[74:75], v[74:75], 0, v[88:89]
	s_waitcnt lgkmcnt(0)
	v_fmamk_f32 v72, v72, 0x3a800000, v146
	v_cmp_gt_f32_e32 vcc, s67, v72
	v_mul_f32_e32 v73, 0x4b800000, v72
	s_nop 0
	v_cndmask_b32_e32 v72, v72, v73, vcc
	v_rsq_f32_e32 v72, v72
	s_nop 0
	v_mul_f32_e32 v73, 0x45800000, v72
	v_cndmask_b32_e32 v72, v72, v73, vcc
	v_pk_mul_f32 v[76:77], v[108:109], v[72:73] op_sel_hi:[1,0]
	v_pk_mul_f32 v[78:79], v[110:111], v[72:73] op_sel_hi:[1,0]
	v_pk_fma_f32 v[76:77], v[174:175], v[76:77], v[128:129]
	v_pk_fma_f32 v[78:79], v[172:173], v[78:79], v[130:131]
	v_cvt_pk_bf16_f32 v76, v76, v77
	s_nop 0
	v_cvt_pk_bf16_f32 v77, v78, v79
	global_store_dwordx2 v[74:75], v[76:77], off
	v_pk_mul_f32 v[76:77], v[124:125], v[72:73] op_sel_hi:[1,0]
	v_pk_mul_f32 v[78:79], v[126:127], v[72:73] op_sel_hi:[1,0]
	v_pk_fma_f32 v[76:77], v[178:179], v[76:77], v[132:133]
	v_pk_fma_f32 v[78:79], v[176:177], v[78:79], v[134:135]
	v_cvt_pk_bf16_f32 v76, v76, v77
	s_nop 0
	v_cvt_pk_bf16_f32 v77, v78, v79
	global_store_dwordx2 v[74:75], v[76:77], off offset:32
	v_pk_mul_f32 v[76:77], v[120:121], v[72:73] op_sel_hi:[1,0]
	v_pk_mul_f32 v[78:79], v[122:123], v[72:73] op_sel_hi:[1,0]
	v_pk_fma_f32 v[76:77], v[182:183], v[76:77], v[136:137]
	v_pk_fma_f32 v[78:79], v[180:181], v[78:79], v[138:139]
	v_cvt_pk_bf16_f32 v76, v76, v77
	s_nop 0
	v_cvt_pk_bf16_f32 v77, v78, v79
	global_store_dwordx2 v[74:75], v[76:77], off offset:256
	v_pk_mul_f32 v[76:77], v[116:117], v[72:73] op_sel_hi:[1,0]
	v_pk_mul_f32 v[72:73], v[118:119], v[72:73] op_sel_hi:[1,0]
	v_pk_fma_f32 v[76:77], v[186:187], v[76:77], v[140:141]
	v_pk_fma_f32 v[72:73], v[184:185], v[72:73], v[142:143]
	v_cvt_pk_bf16_f32 v76, v76, v77
	s_nop 0
	v_cvt_pk_bf16_f32 v77, v72, v73
	global_store_dwordx2 v[74:75], v[76:77], off offset:288
	ds_read_b32 v72, v208 offset:4288
	v_lshlrev_b64 v[74:75], 11, v[162:163]
	v_lshl_add_u64 v[74:75], s[30:31], 0, v[74:75]
	v_lshl_add_u64 v[74:75], v[74:75], 0, v[88:89]
	s_waitcnt lgkmcnt(0)
	v_fmamk_f32 v72, v72, 0x3a800000, v146
	v_cmp_gt_f32_e32 vcc, s67, v72
	v_mul_f32_e32 v73, 0x4b800000, v72
	s_nop 0
	v_cndmask_b32_e32 v72, v72, v73, vcc
	v_rsq_f32_e32 v72, v72
	s_nop 0
	v_mul_f32_e32 v73, 0x45800000, v72
	v_cndmask_b32_e32 v72, v72, v73, vcc
	v_pk_mul_f32 v[76:77], v[112:113], v[72:73] op_sel_hi:[1,0]
	v_pk_mul_f32 v[78:79], v[114:115], v[72:73] op_sel_hi:[1,0]
	v_pk_fma_f32 v[76:77], v[174:175], v[76:77], v[128:129]
	v_pk_fma_f32 v[78:79], v[172:173], v[78:79], v[130:131]
	v_cvt_pk_bf16_f32 v76, v76, v77
	v_pk_mul_f32 v[68:69], v[68:69], v[72:73] op_sel_hi:[1,0]
	v_cvt_pk_bf16_f32 v77, v78, v79
	global_store_dwordx2 v[74:75], v[76:77], off
	v_pk_mul_f32 v[76:77], v[96:97], v[72:73] op_sel_hi:[1,0]
	v_pk_mul_f32 v[64:65], v[64:65], v[72:73] op_sel_hi:[1,0]
	v_pk_mul_f32 v[78:79], v[98:99], v[72:73] op_sel_hi:[1,0]
	v_pk_fma_f32 v[76:77], v[178:179], v[76:77], v[132:133]
	v_pk_mul_f32 v[70:71], v[70:71], v[72:73] op_sel_hi:[1,0]
	v_pk_fma_f32 v[68:69], v[182:183], v[68:69], v[136:137]
	v_pk_mul_f32 v[66:67], v[66:67], v[72:73] op_sel_hi:[1,0]
	v_pk_fma_f32 v[64:65], v[186:187], v[64:65], v[140:141]
	v_pk_fma_f32 v[78:79], v[176:177], v[78:79], v[134:135]
	v_cvt_pk_bf16_f32 v76, v76, v77
	v_pk_fma_f32 v[70:71], v[180:181], v[70:71], v[138:139]
	v_cvt_pk_bf16_f32 v77, v78, v79
	global_store_dwordx2 v[74:75], v[76:77], off offset:32
	v_cvt_pk_bf16_f32 v68, v68, v69
	v_cvt_pk_bf16_f32 v69, v70, v71
	global_store_dwordx2 v[74:75], v[68:69], off offset:256
	v_pk_fma_f32 v[66:67], v[184:185], v[66:67], v[142:143]
	v_cvt_pk_bf16_f32 v64, v64, v65
	s_nop 0
	v_cvt_pk_bf16_f32 v65, v66, v67
	global_store_dwordx2 v[74:75], v[64:65], off offset:288
	ds_read_b32 v64, v208 offset:4608
	v_lshlrev_b64 v[66:67], 11, v[164:165]
	s_waitcnt lgkmcnt(0)
; __device__ __forceinline__ unsigned cvt_pk_bf16(float lo, float hi) { unsigned r; asm volatile("v_cvt_pk_bf16_f32 %0, %1, %2" : "=v"(r) : "v"(lo), "v"(hi)); return r; }
;     __device__ __forceinline__ void fused(f32x4 (&acc)[2][2][4][2], const Unit& u, int wr, int wc, int fr, int fq, LAS unsigned char* lds, int wid, int lane) const {
;     ...
;             for (int ai = 0; ai < 2; ++ai)
; #pragma unroll
;                 for (int m = 0; m < 4; ++m) { const int r = ai * HALF + wr * 64 + m * 16 + fr; const float r2 = rsqrtf(S[r] * (1.0f / D) + EPS); const size_t off = (size_t)(u.pm * BM + r) * D + col0;
; #pragma unroll
;                     for (int bj = 0; bj < 2; ++bj)
; #pragma unroll
;                         for (int n = 0; n < 2; ++n) { const f32x4 hv = (acc[ai][bj][m][n] * r2) * gm[bj][n] + sh[bj][n];
;                             uint2 w2; w2.x = cvt_pk_bf16(hv[0], hv[1]); w2.y = cvt_pk_bf16(hv[2], hv[3]); *(uint2*)(H + off + bj * HALF + n * 16) = w2; }
;                     asm volatile("" ::: "memory"); }
	v_fmamk_f32 v64, v64, 0x3a800000, v146
	v_cmp_gt_f32_e32 vcc, s67, v64
	v_mul_f32_e32 v65, 0x4b800000, v64
	s_nop 0
	v_cndmask_b32_e32 v64, v64, v65, vcc
	v_rsq_f32_e32 v64, v64
	s_nop 0
	v_mul_f32_e32 v65, 0x45800000, v64
	v_cndmask_b32_e32 v64, v64, v65, vcc
	v_pk_mul_f32 v[60:61], v[60:61], v[64:65] op_sel_hi:[1,0]
	v_pk_mul_f32 v[62:63], v[62:63], v[64:65] op_sel_hi:[1,0]
	v_pk_fma_f32 v[60:61], v[174:175], v[60:61], v[128:129]
	v_pk_fma_f32 v[62:63], v[172:173], v[62:63], v[130:131]
	v_cvt_pk_bf16_f32 v60, v60, v61
	v_pk_mul_f32 v[56:57], v[56:57], v[64:65] op_sel_hi:[1,0]
	v_cvt_pk_bf16_f32 v61, v62, v63
	v_lshl_add_u64 v[62:63], s[30:31], 0, v[66:67]
	v_pk_mul_f32 v[52:53], v[52:53], v[64:65] op_sel_hi:[1,0]
	v_pk_mul_f32 v[48:49], v[48:49], v[64:65] op_sel_hi:[1,0]
	v_lshl_add_u64 v[62:63], v[62:63], 0, v[88:89]
	v_pk_mul_f32 v[58:59], v[58:59], v[64:65] op_sel_hi:[1,0]
	v_pk_fma_f32 v[56:57], v[178:179], v[56:57], v[132:133]
	v_pk_mul_f32 v[54:55], v[54:55], v[64:65] op_sel_hi:[1,0]
	v_pk_fma_f32 v[52:53], v[182:183], v[52:53], v[136:137]
	v_pk_mul_f32 v[50:51], v[50:51], v[64:65] op_sel_hi:[1,0]
	v_pk_fma_f32 v[48:49], v[186:187], v[48:49], v[140:141]
	global_store_dwordx2 v[62:63], v[60:61], off
	v_pk_fma_f32 v[58:59], v[176:177], v[58:59], v[134:135]
	v_cvt_pk_bf16_f32 v56, v56, v57
	v_pk_fma_f32 v[54:55], v[180:181], v[54:55], v[138:139]
	v_cvt_pk_bf16_f32 v57, v58, v59
	global_store_dwordx2 v[62:63], v[56:57], off offset:32
	v_cvt_pk_bf16_f32 v52, v52, v53
	v_cvt_pk_bf16_f32 v53, v54, v55
	global_store_dwordx2 v[62:63], v[52:53], off offset:256
	v_pk_fma_f32 v[50:51], v[184:185], v[50:51], v[142:143]
	v_cvt_pk_bf16_f32 v48, v48, v49
	s_nop 0
	v_cvt_pk_bf16_f32 v49, v50, v51
	global_store_dwordx2 v[62:63], v[48:49], off offset:288
	ds_read_b32 v48, v208 offset:4672
	v_lshlrev_b64 v[50:51], 11, v[166:167]
	s_waitcnt lgkmcnt(0)
	v_fmamk_f32 v48, v48, 0x3a800000, v146
	v_cmp_gt_f32_e32 vcc, s67, v48
	v_mul_f32_e32 v49, 0x4b800000, v48
	s_nop 0
	v_cndmask_b32_e32 v48, v48, v49, vcc
	v_rsq_f32_e32 v48, v48
	s_nop 0
	v_mul_f32_e32 v49, 0x45800000, v48
	v_cndmask_b32_e32 v48, v48, v49, vcc
	v_pk_mul_f32 v[44:45], v[44:45], v[48:49] op_sel_hi:[1,0]
	v_pk_mul_f32 v[46:47], v[46:47], v[48:49] op_sel_hi:[1,0]
	v_pk_fma_f32 v[44:45], v[174:175], v[44:45], v[128:129]
	v_pk_fma_f32 v[46:47], v[172:173], v[46:47], v[130:131]
	v_cvt_pk_bf16_f32 v44, v44, v45
	v_pk_mul_f32 v[40:41], v[40:41], v[48:49] op_sel_hi:[1,0]
	v_cvt_pk_bf16_f32 v45, v46, v47
	v_lshl_add_u64 v[46:47], s[30:31], 0, v[50:51]
	v_pk_mul_f32 v[36:37], v[36:37], v[48:49] op_sel_hi:[1,0]
	v_pk_mul_f32 v[32:33], v[32:33], v[48:49] op_sel_hi:[1,0]
	v_lshl_add_u64 v[46:47], v[46:47], 0, v[88:89]
	v_pk_mul_f32 v[42:43], v[42:43], v[48:49] op_sel_hi:[1,0]
	v_pk_fma_f32 v[40:41], v[178:179], v[40:41], v[132:133]
	v_pk_mul_f32 v[38:39], v[38:39], v[48:49] op_sel_hi:[1,0]
	v_pk_fma_f32 v[36:37], v[182:183], v[36:37], v[136:137]
	v_pk_mul_f32 v[34:35], v[34:35], v[48:49] op_sel_hi:[1,0]
	v_pk_fma_f32 v[32:33], v[186:187], v[32:33], v[140:141]
	global_store_dwordx2 v[46:47], v[44:45], off
	v_pk_fma_f32 v[42:43], v[176:177], v[42:43], v[134:135]
	v_cvt_pk_bf16_f32 v40, v40, v41
	v_pk_fma_f32 v[38:39], v[180:181], v[38:39], v[138:139]
	v_cvt_pk_bf16_f32 v41, v42, v43
	global_store_dwordx2 v[46:47], v[40:41], off offset:32
	v_cvt_pk_bf16_f32 v36, v36, v37
	v_cvt_pk_bf16_f32 v37, v38, v39
	global_store_dwordx2 v[46:47], v[36:37], off offset:256
	v_pk_fma_f32 v[34:35], v[184:185], v[34:35], v[142:143]
	v_cvt_pk_bf16_f32 v32, v32, v33
	s_nop 0
	v_cvt_pk_bf16_f32 v33, v34, v35
	global_store_dwordx2 v[46:47], v[32:33], off offset:288
	ds_read_b32 v32, v208 offset:4736
	v_lshlrev_b64 v[34:35], 11, v[168:169]
	s_waitcnt lgkmcnt(0)
; __device__ __forceinline__ unsigned cvt_pk_bf16(float lo, float hi) { unsigned r; asm volatile("v_cvt_pk_bf16_f32 %0, %1, %2" : "=v"(r) : "v"(lo), "v"(hi)); return r; }
;     __device__ __forceinline__ void fused(f32x4 (&acc)[2][2][4][2], const Unit& u, int wr, int wc, int fr, int fq, LAS unsigned char* lds, int wid, int lane) const {
;     ...
;             for (int ai = 0; ai < 2; ++ai)
; #pragma unroll
;                 for (int m = 0; m < 4; ++m) { const int r = ai * HALF + wr * 64 + m * 16 + fr; const float r2 = rsqrtf(S[r] * (1.0f / D) + EPS); const size_t off = (size_t)(u.pm * BM + r) * D + col0;
; #pragma unroll
;                     for (int bj = 0; bj < 2; ++bj)
; #pragma unroll
;                         for (int n = 0; n < 2; ++n) { const f32x4 hv = (acc[ai][bj][m][n] * r2) * gm[bj][n] + sh[bj][n];
;                             uint2 w2; w2.x = cvt_pk_bf16(hv[0], hv[1]); w2.y = cvt_pk_bf16(hv[2], hv[3]); *(uint2*)(H + off + bj * HALF + n * 16) = w2; }
;                     asm volatile("" ::: "memory"); }
	v_fmamk_f32 v32, v32, 0x3a800000, v146
	v_cmp_gt_f32_e32 vcc, s67, v32
	v_mul_f32_e32 v33, 0x4b800000, v32
	s_nop 0
	v_cndmask_b32_e32 v32, v32, v33, vcc
	v_rsq_f32_e32 v32, v32
	s_nop 0
	v_mul_f32_e32 v33, 0x45800000, v32
	v_cndmask_b32_e32 v32, v32, v33, vcc
	v_pk_mul_f32 v[28:29], v[28:29], v[32:33] op_sel_hi:[1,0]
	v_pk_mul_f32 v[30:31], v[30:31], v[32:33] op_sel_hi:[1,0]
	v_pk_fma_f32 v[28:29], v[174:175], v[28:29], v[128:129]
	v_pk_fma_f32 v[30:31], v[172:173], v[30:31], v[130:131]
	v_cvt_pk_bf16_f32 v28, v28, v29
	v_pk_mul_f32 v[24:25], v[24:25], v[32:33] op_sel_hi:[1,0]
	v_cvt_pk_bf16_f32 v29, v30, v31
	v_lshl_add_u64 v[30:31], s[30:31], 0, v[34:35]
	v_pk_mul_f32 v[20:21], v[20:21], v[32:33] op_sel_hi:[1,0]
	v_pk_mul_f32 v[16:17], v[16:17], v[32:33] op_sel_hi:[1,0]
	v_lshl_add_u64 v[30:31], v[30:31], 0, v[88:89]
	v_pk_mul_f32 v[26:27], v[26:27], v[32:33] op_sel_hi:[1,0]
	v_pk_fma_f32 v[24:25], v[178:179], v[24:25], v[132:133]
	v_pk_mul_f32 v[22:23], v[22:23], v[32:33] op_sel_hi:[1,0]
	v_pk_fma_f32 v[20:21], v[182:183], v[20:21], v[136:137]
	v_pk_mul_f32 v[18:19], v[18:19], v[32:33] op_sel_hi:[1,0]
	v_pk_fma_f32 v[16:17], v[186:187], v[16:17], v[140:141]
	global_store_dwordx2 v[30:31], v[28:29], off
	v_pk_fma_f32 v[26:27], v[176:177], v[26:27], v[134:135]
	v_cvt_pk_bf16_f32 v24, v24, v25
	v_pk_fma_f32 v[22:23], v[180:181], v[22:23], v[138:139]
	v_cvt_pk_bf16_f32 v25, v26, v27
	global_store_dwordx2 v[30:31], v[24:25], off offset:32
	v_cvt_pk_bf16_f32 v20, v20, v21
	v_cvt_pk_bf16_f32 v21, v22, v23
	global_store_dwordx2 v[30:31], v[20:21], off offset:256
	v_pk_fma_f32 v[18:19], v[184:185], v[18:19], v[142:143]
	v_cvt_pk_bf16_f32 v16, v16, v17
	s_nop 0
	v_cvt_pk_bf16_f32 v17, v18, v19
	global_store_dwordx2 v[30:31], v[16:17], off offset:288
	ds_read_b32 v16, v208 offset:4800
	v_lshlrev_b64 v[18:19], 11, v[170:171]
	s_waitcnt lgkmcnt(0)
	v_fmamk_f32 v16, v16, 0x3a800000, v146
	v_cmp_gt_f32_e32 vcc, s67, v16
	v_mul_f32_e32 v17, 0x4b800000, v16
	s_nop 0
	v_cndmask_b32_e32 v16, v16, v17, vcc
	v_rsq_f32_e32 v16, v16
	s_nop 0
	v_mul_f32_e32 v17, 0x45800000, v16
	v_cndmask_b32_e32 v16, v16, v17, vcc
	v_pk_mul_f32 v[12:13], v[12:13], v[16:17] op_sel_hi:[1,0]
	v_pk_mul_f32 v[14:15], v[14:15], v[16:17] op_sel_hi:[1,0]
	v_pk_fma_f32 v[12:13], v[174:175], v[12:13], v[128:129]
	v_pk_fma_f32 v[14:15], v[172:173], v[14:15], v[130:131]
	v_cvt_pk_bf16_f32 v12, v12, v13
	v_pk_mul_f32 v[8:9], v[8:9], v[16:17] op_sel_hi:[1,0]
	v_cvt_pk_bf16_f32 v13, v14, v15
	v_lshl_add_u64 v[14:15], s[30:31], 0, v[18:19]
	v_pk_mul_f32 v[4:5], v[4:5], v[16:17] op_sel_hi:[1,0]
	v_pk_mul_f32 v[0:1], v[0:1], v[16:17] op_sel_hi:[1,0]
	v_lshl_add_u64 v[14:15], v[14:15], 0, v[88:89]
	v_pk_mul_f32 v[10:11], v[10:11], v[16:17] op_sel_hi:[1,0]
	v_pk_fma_f32 v[8:9], v[178:179], v[8:9], v[132:133]
	v_pk_mul_f32 v[6:7], v[6:7], v[16:17] op_sel_hi:[1,0]
	v_pk_fma_f32 v[4:5], v[182:183], v[4:5], v[136:137]
	v_pk_mul_f32 v[2:3], v[2:3], v[16:17] op_sel_hi:[1,0]
	v_pk_fma_f32 v[0:1], v[186:187], v[0:1], v[140:141]
	global_store_dwordx2 v[14:15], v[12:13], off
	v_pk_fma_f32 v[10:11], v[176:177], v[10:11], v[134:135]
	v_cvt_pk_bf16_f32 v8, v8, v9
	v_pk_fma_f32 v[6:7], v[180:181], v[6:7], v[138:139]
	v_cvt_pk_bf16_f32 v9, v10, v11
	global_store_dwordx2 v[14:15], v[8:9], off offset:32
	v_cvt_pk_bf16_f32 v4, v4, v5
	v_cvt_pk_bf16_f32 v5, v6, v7
	global_store_dwordx2 v[14:15], v[4:5], off offset:256
	v_pk_fma_f32 v[2:3], v[184:185], v[2:3], v[142:143]
	v_cvt_pk_bf16_f32 v0, v0, v1
	s_nop 0
	v_cvt_pk_bf16_f32 v1, v2, v3
	global_store_dwordx2 v[14:15], v[0:1], off offset:288
	s_waitcnt vmcnt(29)
